# finer phase overlap: phase 0 converts only layer-0 FFN1 weights; FFN1-down tail converts the rest of the same layer, FFN2-down tail converts next layer's FFN1 weights; plus GEMV rewrite
# speedup vs baseline: 1.0166x; 1.0020x over previous
; #define LAS __attribute__((address_space(3)))
; __device__ __forceinline__ int tid_opaque() { int t = threadIdx.x; asm volatile("" : "+v"(t)); return t; }
; __device__ void phase_setup(const Params& p, LAS unsigned char* lds) {
;     const int tid = tid_opaque(), wid = tid >> 6, lane = tid & 63;
;     bf16_t* WT = (bf16_t*)(p.ws + WS_WT);
;     LAS float* tl = (LAS float*)lds;
;     for (int l = 0; l < NL; ++l) {
;         bf16_t* W = WT + (size_t)l * W_LAYER;
;         for (int j = 0; j < 2; ++j) {
;             tr_job(tl, p.in[I_FFNIN] + ((size_t)l * 2 + j) * D * (2 * DFF), 2 * DFF, D, 2 * DFF, W + (j ? W_FIN1 : W_FIN0), D, 0, 1);
;             tr_job(tl, p.in[I_FFNOUT] + ((size_t)l * 2 + j) * DFF * D, D, DFF, D, W + (j ? W_FOUT1 : W_FOUT0), DFF, 0, 0);
;         }
;         tr_job(tl, p.in[I_WIN] + (size_t)l * D * PROJ, PROJ, D, PROJ, W + W_WIN, D, 0, 0);
;         tr_job(tl, p.in[I_WBC] + (size_t)l * 256 * D, D, 256, D, W + W_WB, D, 0, 0);
;         tr_job(tl, p.in[I_WBG] + (size_t)l * 256 * D, D, 256, D, W + W_WB, D, 256, 0);
;         tr_job(tl, p.in[I_WBA] + (size_t)l * 512 * D, D, 512, D, W + W_WB, D, 512, 0);
;         tr_job(tl, p.in[I_WOUT] + (size_t)l * D * D, D, D, D, W + W_WO, D, 0, 0);
.LBB0_383:
	s_and_b64 vcc, exec, s[0:1]
	s_cbranch_vccz .LBB0_466
	s_waitcnt vmcnt(0)
	s_load_dword s10, s[94:95], 0x0
	s_waitcnt lgkmcnt(0)
	s_max_u32 s10, s10, 1
	s_mov_b32 s15, 24064
	s_mov_b32 s11, s2
	s_mov_b32 s86, 0
	s_cmp_eq_u32 s10, 256
	s_cbranch_scc0 .Lmytr_entry
	s_movk_i32 s15, 2112
	s_mov_b32 s11, 2112
	s_cmp_ge_u32 s2, 144
	s_cbranch_scc0 .Lmytr_entry
	s_sub_u32 s11, s2, 144
	s_movk_i32 s10, 112

; __device__ void phase_setup(const Params& p, LAS unsigned char* lds) {
;     ...
;     for (int l = 0; l < NL; ++l) {
;         bf16_t* W = WT + (size_t)l * W_LAYER;
;         for (int j = 0; j < 2; ++j) {
;             tr_job(tl, p.in[I_FFNIN] + ((size_t)l * 2 + j) * D * (2 * DFF), 2 * DFF, D, 2 * DFF, W + (j ? W_FIN1 : W_FIN0), D, 0, 1);
;             tr_job(tl, p.in[I_FFNOUT] + ((size_t)l * 2 + j) * DFF * D, D, DFF, D, W + (j ? W_FOUT1 : W_FOUT0), DFF, 0, 0);
;         }
;         tr_job(tl, p.in[I_WIN] + (size_t)l * D * PROJ, PROJ, D, PROJ, W + W_WIN, D, 0, 0);
;         tr_job(tl, p.in[I_WBC] + (size_t)l * 256 * D, D, 256, D, W + W_WB, D, 0, 0);
;         tr_job(tl, p.in[I_WBG] + (size_t)l * 256 * D, D, 256, D, W + W_WB, D, 256, 0);
;         tr_job(tl, p.in[I_WBA] + (size_t)l * 512 * D, D, 512, D, W + W_WB, D, 512, 0);
;         tr_job(tl, p.in[I_WOUT] + (size_t)l * D * D, D, D, D, W + W_WO, D, 0, 0);
; __device__ void run_phase(const Params& p, int ph, LAS unsigned char* lds) {
;     ...
;     if (r == 2 || r == 16) {
;         const int j = (r == 2) ? 0 : 1;
;         const int sk = (lastl && j == 1) ? 1 : 0;
;         pg8::Gemm g{R1, DFF, W + (j ? W_FOUT1 : W_FOUT0), DFF, sk ? T_LAT : T_ALL, D, DFF, sk, 1};
;         const int nj = (r == 2) ? 1 : (lastl ? -1 : 0), ln = (r == 2) ? l : l + 1;
;         const bool fin = (lastl && r == 16);
;         const float* ngp = p.in[I_NORMG] + ((size_t)(nj < 0 ? 0 : ln) * 3 + (nj < 0 ? 0 : nj)) * D; const float* nmp = (const float*)(p.ws + WS_MOD) + (size_t)(nj < 0 ? 0 : ln) * 33 * (NMOD * D);
;         unsigned* cntp = (unsigned*)(p.ws + WS_CNT) + (size_t)(l * 3 + (r == 2 ? 0 : 2)) * 576;
;     ...
;         if (fin) { pg8::EpiResid<2, false> E{p.in[I_X], p.in[I_CTX], HB, p.out, MOD, 8, 0.5f, 0, 2, -1, ngp, nmp, A, (float*)(p.ws + WS_XS), cntp, lds}; pg8::gemm_phase(lds, g, E); }
;         else { pg8::EpiResid<1, true> E{p.in[I_X], p.in[I_CTX], HB, p.out, MOD, j ? 8 : 2, 0.5f, 0, 1, nj, ngp, nmp, A, (float*)(p.ws + WS_XS), cntp, lds}; pg8::gemm_phase(lds, g, E); }
;     ...
;         return;
.LBB0_466:
	v_readlane_b32 s11, v254, 30
	s_cmp_lt_i32 s11, 1
	s_cbranch_scc1 .Lmytr_skipB
	s_cmp_ge_u32 s2, 128
	s_cbranch_scc0 .Lmytr_skipB
	s_add_i32 s0, s11, -1
	s_mul_hi_i32 s1, s0, 0x78787879
	s_lshr_b32 s4, s1, 31
	s_ashr_i32 s1, s1, 3
	s_add_i32 s1, s1, s4
	s_mul_i32 s4, s1, 17
	s_sub_i32 s0, s0, s4
	s_mul_i32 s15, s1, 6016
	s_cmp_eq_u32 s0, 2
	s_cbranch_scc1 .Lmytr_B2
	s_cmp_eq_u32 s0, 16
	s_cbranch_scc0 .Lmytr_skipB
	s_cmp_lt_u32 s1, 3
	s_cbranch_scc0 .Lmytr_skipB
	s_add_u32 s11, s15, 6016
	s_add_u32 s15, s11, 2112
	s_branch .Lmytr_Bgo
.Lmytr_B2:
	s_add_u32 s11, s15, 2112
	s_add_u32 s15, s15, 6016
.Lmytr_Bgo:
	v_readlane_b32 s94, v254, 9
	v_readlane_b32 s95, v254, 10
	s_nop 3
	s_load_dword s10, s[94:95], 0x0
	s_waitcnt lgkmcnt(0)
	s_cmp_eq_u32 s10, 256
	s_cbranch_scc0 .Lmytr_skipB0
	s_add_u32 s11, s11, s2
	s_sub_u32 s11, s11, 128
	s_movk_i32 s10, 128
	s_mov_b32 s86, 1
	s_waitcnt vmcnt(0) lgkmcnt(0)
	s_barrier
	s_branch .Lmytr_entry
.Lmytr_ret1:
	s_barrier
.Lmytr_skipB0:
	v_readlane_b32 s11, v254, 30
.Lmytr_skipB:
	s_add_i32 s84, s11, 1
	v_readlane_b32 s0, v254, 27
	s_cmp_ge_i32 s84, s0
	s_cbranch_scc0 .LBB0_467
	s_getpc_b64 s[98:99]
